# scan waves: hand-scheduled 16-step block, LDS operand reads of step s+1 issued as one burst at the top of step s (same math, same op order)
# speedup vs baseline: 1.0136x; 1.0063x over previous
.LBB0_650:
	s_andn2_saveexec_b64 s[46:47], s[46:47]
	s_cbranch_execz .LBB0_652
	v_add_u32_e32 v136, 0xa000, v95
	ds_read_b128 v[28:31], v92 offset:256
	ds_read_b128 v[102:105], v92 offset:768
	ds_read_b128 v[24:27], v92 offset:0
	ds_read_b128 v[98:101], v92 offset:512
	ds_read_b128 v[106:109], v92 offset:1024
	ds_read2_b32 v[130:131], v136 offset0:0 offset1:16
	ds_read_b128 v[114:117], v92 offset:1536
	ds_read_b128 v[122:125], v92 offset:2048
	ds_read_b128 v[110:113], v92 offset:1280
	ds_read_b128 v[118:121], v92 offset:1792
	ds_read_b128 v[126:129], v92 offset:2304
	s_waitcnt lgkmcnt(5)
	v_pk_mul_f32 v[36:37], v[90:91], v[28:29]
	v_pk_fma_f32 v[36:37], v[88:89], v[30:31], v[36:37]
	v_add_f32_e32 v38, v36, v37
	v_pk_mul_f32 v[40:41], v[102:103], v[130:131] op_sel_hi:[1,0]
	v_pk_mul_f32 v[42:43], v[104:105], v[130:131] op_sel_hi:[1,0]
	v_add_f32_dpp v38, v38, v38 quad_perm:[1,0,3,2] row_mask:0xf bank_mask:0xf bound_ctrl:1
	v_pk_fma_f32 v[40:41], v[90:91], v[24:25], v[40:41]
	v_pk_fma_f32 v[42:43], v[88:89], v[26:27], v[42:43]
	v_add_f32_dpp v38, v38, v38 quad_perm:[2,3,0,1] row_mask:0xf bank_mask:0xf bound_ctrl:1
	s_nop 1
	v_add_f32_dpp v38, v38, v38 row_half_mirror row_mask:0xf bank_mask:0xf bound_ctrl:1
	s_nop 1
	v_add_f32_dpp v38, v38, v38 row_mirror row_mask:0xf bank_mask:0xf bound_ctrl:1
	v_pk_fma_f32 v[90:91], v[98:99], v[38:39], v[40:41] op_sel_hi:[1,0,1]
	v_pk_fma_f32 v[88:89], v[100:101], v[38:39], v[42:43] op_sel_hi:[1,0,1]
	ds_read_b128 v[28:31], v92 offset:2816
	ds_read_b128 v[102:105], v92 offset:3328
	ds_read_b128 v[24:27], v92 offset:2560
	ds_read_b128 v[98:101], v92 offset:3072
	ds_read_b128 v[50:53], v92 offset:3584
	ds_read2_b32 v[132:133], v136 offset0:32 offset1:48
	s_waitcnt lgkmcnt(6)
	v_pk_mul_f32 v[36:37], v[90:91], v[114:115]
	v_pk_fma_f32 v[36:37], v[88:89], v[116:117], v[36:37]
	v_add_f32_e32 v38, v36, v37
	v_pk_mul_f32 v[40:41], v[122:123], v[130:131] op_sel:[0,1] op_sel_hi:[1,1]
	v_pk_mul_f32 v[42:43], v[124:125], v[130:131] op_sel:[0,1] op_sel_hi:[1,1]
	v_add_f32_dpp v38, v38, v38 quad_perm:[1,0,3,2] row_mask:0xf bank_mask:0xf bound_ctrl:1
	v_pk_fma_f32 v[40:41], v[90:91], v[110:111], v[40:41]
	v_pk_fma_f32 v[42:43], v[88:89], v[112:113], v[42:43]
	v_add_f32_dpp v38, v38, v38 quad_perm:[2,3,0,1] row_mask:0xf bank_mask:0xf bound_ctrl:1
	v_pk_mul_f32 v[44:45], v[90:91], v[106:107]
	v_pk_fma_f32 v[44:45], v[88:89], v[108:109], v[44:45]
	v_add_f32_dpp v38, v38, v38 row_half_mirror row_mask:0xf bank_mask:0xf bound_ctrl:1
	v_add_f32_e32 v46, v44, v45
	s_nop 0
	v_add_f32_dpp v38, v38, v38 row_mirror row_mask:0xf bank_mask:0xf bound_ctrl:1
	v_pk_fma_f32 v[90:91], v[118:119], v[38:39], v[40:41] op_sel_hi:[1,0,1]
	v_pk_fma_f32 v[88:89], v[120:121], v[38:39], v[42:43] op_sel_hi:[1,0,1]
	ds_read_b128 v[114:117], v92 offset:4096
	ds_read_b128 v[122:125], v92 offset:4608
	ds_read_b128 v[110:113], v92 offset:3840
	ds_read_b128 v[118:121], v92 offset:4352
	ds_read_b128 v[54:57], v92 offset:4864
	s_waitcnt lgkmcnt(5)
	v_pk_mul_f32 v[36:37], v[90:91], v[28:29]
	v_pk_fma_f32 v[36:37], v[88:89], v[30:31], v[36:37]
	v_add_f32_e32 v38, v36, v37
	v_pk_mul_f32 v[40:41], v[102:103], v[132:133] op_sel_hi:[1,0]
	v_pk_mul_f32 v[42:43], v[104:105], v[132:133] op_sel_hi:[1,0]
	v_add_f32_dpp v38, v38, v38 quad_perm:[1,0,3,2] row_mask:0xf bank_mask:0xf bound_ctrl:1
	v_pk_fma_f32 v[40:41], v[90:91], v[24:25], v[40:41]
	v_pk_fma_f32 v[42:43], v[88:89], v[26:27], v[42:43]
	v_add_f32_dpp v38, v38, v38 quad_perm:[2,3,0,1] row_mask:0xf bank_mask:0xf bound_ctrl:1
	v_pk_mul_f32 v[44:45], v[90:91], v[126:127]
	v_pk_fma_f32 v[44:45], v[88:89], v[128:129], v[44:45]
	v_add_f32_dpp v38, v38, v38 row_half_mirror row_mask:0xf bank_mask:0xf bound_ctrl:1
	v_add_f32_e32 v47, v44, v45
	s_nop 0
	v_add_f32_dpp v38, v38, v38 row_mirror row_mask:0xf bank_mask:0xf bound_ctrl:1
	v_pk_fma_f32 v[90:91], v[98:99], v[38:39], v[40:41] op_sel_hi:[1,0,1]
	v_pk_fma_f32 v[88:89], v[100:101], v[38:39], v[42:43] op_sel_hi:[1,0,1]
	ds_read_b128 v[28:31], v92 offset:5376
	ds_read_b128 v[102:105], v92 offset:5888
	ds_read_b128 v[24:27], v92 offset:5120
	ds_read_b128 v[98:101], v92 offset:5632
	ds_read_b128 v[106:109], v92 offset:6144
	ds_read2_b32 v[130:131], v136 offset0:64 offset1:80
	ds_write2st64_b32 v96, v46, v47 offset0:168 offset1:172
	s_waitcnt lgkmcnt(7)
	v_pk_mul_f32 v[36:37], v[90:91], v[114:115]
	v_pk_fma_f32 v[36:37], v[88:89], v[116:117], v[36:37]
	v_add_f32_e32 v38, v36, v37
	v_pk_mul_f32 v[40:41], v[122:123], v[132:133] op_sel:[0,1] op_sel_hi:[1,1]
	v_pk_mul_f32 v[42:43], v[124:125], v[132:133] op_sel:[0,1] op_sel_hi:[1,1]
	v_add_f32_dpp v38, v38, v38 quad_perm:[1,0,3,2] row_mask:0xf bank_mask:0xf bound_ctrl:1
	v_pk_fma_f32 v[40:41], v[90:91], v[110:111], v[40:41]
	v_pk_fma_f32 v[42:43], v[88:89], v[112:113], v[42:43]
	v_add_f32_dpp v38, v38, v38 quad_perm:[2,3,0,1] row_mask:0xf bank_mask:0xf bound_ctrl:1
	v_pk_mul_f32 v[44:45], v[90:91], v[50:51]
	v_pk_fma_f32 v[44:45], v[88:89], v[52:53], v[44:45]
	v_add_f32_dpp v38, v38, v38 row_half_mirror row_mask:0xf bank_mask:0xf bound_ctrl:1
	v_add_f32_e32 v48, v44, v45
	s_nop 0
	v_add_f32_dpp v38, v38, v38 row_mirror row_mask:0xf bank_mask:0xf bound_ctrl:1
	v_pk_fma_f32 v[90:91], v[118:119], v[38:39], v[40:41] op_sel_hi:[1,0,1]
	v_pk_fma_f32 v[88:89], v[120:121], v[38:39], v[42:43] op_sel_hi:[1,0,1]
	ds_read_b128 v[114:117], v92 offset:6656
	ds_read_b128 v[122:125], v92 offset:7168
	ds_read_b128 v[110:113], v92 offset:6400
	ds_read_b128 v[118:121], v92 offset:6912
	ds_read_b128 v[126:129], v92 offset:7424
	s_waitcnt lgkmcnt(5)
	v_pk_mul_f32 v[36:37], v[90:91], v[28:29]
	v_pk_fma_f32 v[36:37], v[88:89], v[30:31], v[36:37]
	v_add_f32_e32 v38, v36, v37
	v_pk_mul_f32 v[40:41], v[102:103], v[130:131] op_sel_hi:[1,0]
	v_pk_mul_f32 v[42:43], v[104:105], v[130:131] op_sel_hi:[1,0]
	v_add_f32_dpp v38, v38, v38 quad_perm:[1,0,3,2] row_mask:0xf bank_mask:0xf bound_ctrl:1
	v_pk_fma_f32 v[40:41], v[90:91], v[24:25], v[40:41]
	v_pk_fma_f32 v[42:43], v[88:89], v[26:27], v[42:43]
	v_add_f32_dpp v38, v38, v38 quad_perm:[2,3,0,1] row_mask:0xf bank_mask:0xf bound_ctrl:1
	v_pk_mul_f32 v[44:45], v[90:91], v[54:55]
	v_pk_fma_f32 v[44:45], v[88:89], v[56:57], v[44:45]
	v_add_f32_dpp v38, v38, v38 row_half_mirror row_mask:0xf bank_mask:0xf bound_ctrl:1
	v_add_f32_e32 v49, v44, v45
	s_nop 0
	v_add_f32_dpp v38, v38, v38 row_mirror row_mask:0xf bank_mask:0xf bound_ctrl:1
	v_pk_fma_f32 v[90:91], v[98:99], v[38:39], v[40:41] op_sel_hi:[1,0,1]
	v_pk_fma_f32 v[88:89], v[100:101], v[38:39], v[42:43] op_sel_hi:[1,0,1]
	ds_read_b128 v[28:31], v92 offset:7936
	ds_read_b128 v[102:105], v92 offset:8448
	ds_read_b128 v[24:27], v92 offset:7680
	ds_read_b128 v[98:101], v92 offset:8192
	ds_read_b128 v[50:53], v92 offset:8704
	ds_read2_b32 v[132:133], v136 offset0:96 offset1:112
	ds_write2st64_b32 v96, v48, v49 offset0:176 offset1:180
	s_waitcnt lgkmcnt(7)
	v_pk_mul_f32 v[36:37], v[90:91], v[114:115]
	v_pk_fma_f32 v[36:37], v[88:89], v[116:117], v[36:37]
	v_add_f32_e32 v38, v36, v37
	v_pk_mul_f32 v[40:41], v[122:123], v[130:131] op_sel:[0,1] op_sel_hi:[1,1]
	v_pk_mul_f32 v[42:43], v[124:125], v[130:131] op_sel:[0,1] op_sel_hi:[1,1]
	v_add_f32_dpp v38, v38, v38 quad_perm:[1,0,3,2] row_mask:0xf bank_mask:0xf bound_ctrl:1
	v_pk_fma_f32 v[40:41], v[90:91], v[110:111], v[40:41]
	v_pk_fma_f32 v[42:43], v[88:89], v[112:113], v[42:43]
	v_add_f32_dpp v38, v38, v38 quad_perm:[2,3,0,1] row_mask:0xf bank_mask:0xf bound_ctrl:1
	v_pk_mul_f32 v[44:45], v[90:91], v[106:107]
	v_pk_fma_f32 v[44:45], v[88:89], v[108:109], v[44:45]
	v_add_f32_dpp v38, v38, v38 row_half_mirror row_mask:0xf bank_mask:0xf bound_ctrl:1
	v_add_f32_e32 v46, v44, v45
	s_nop 0
	v_add_f32_dpp v38, v38, v38 row_mirror row_mask:0xf bank_mask:0xf bound_ctrl:1
	v_pk_fma_f32 v[90:91], v[118:119], v[38:39], v[40:41] op_sel_hi:[1,0,1]
	v_pk_fma_f32 v[88:89], v[120:121], v[38:39], v[42:43] op_sel_hi:[1,0,1]
	ds_read_b128 v[114:117], v92 offset:9216
	ds_read_b128 v[122:125], v92 offset:9728
	ds_read_b128 v[110:113], v92 offset:8960
	ds_read_b128 v[118:121], v92 offset:9472
	ds_read_b128 v[54:57], v92 offset:9984
	s_waitcnt lgkmcnt(5)
	v_pk_mul_f32 v[36:37], v[90:91], v[28:29]
	v_pk_fma_f32 v[36:37], v[88:89], v[30:31], v[36:37]
	v_add_f32_e32 v38, v36, v37
	v_pk_mul_f32 v[40:41], v[102:103], v[132:133] op_sel_hi:[1,0]
	v_pk_mul_f32 v[42:43], v[104:105], v[132:133] op_sel_hi:[1,0]
	v_add_f32_dpp v38, v38, v38 quad_perm:[1,0,3,2] row_mask:0xf bank_mask:0xf bound_ctrl:1
	v_pk_fma_f32 v[40:41], v[90:91], v[24:25], v[40:41]
	v_pk_fma_f32 v[42:43], v[88:89], v[26:27], v[42:43]
	v_add_f32_dpp v38, v38, v38 quad_perm:[2,3,0,1] row_mask:0xf bank_mask:0xf bound_ctrl:1
	v_pk_mul_f32 v[44:45], v[90:91], v[126:127]
	v_pk_fma_f32 v[44:45], v[88:89], v[128:129], v[44:45]
	v_add_f32_dpp v38, v38, v38 row_half_mirror row_mask:0xf bank_mask:0xf bound_ctrl:1
	v_add_f32_e32 v47, v44, v45
	s_nop 0
	v_add_f32_dpp v38, v38, v38 row_mirror row_mask:0xf bank_mask:0xf bound_ctrl:1
	v_pk_fma_f32 v[90:91], v[98:99], v[38:39], v[40:41] op_sel_hi:[1,0,1]
	v_pk_fma_f32 v[88:89], v[100:101], v[38:39], v[42:43] op_sel_hi:[1,0,1]
	ds_read_b128 v[28:31], v92 offset:10496
	ds_read_b128 v[102:105], v92 offset:11008
	ds_read_b128 v[24:27], v92 offset:10240
	ds_read_b128 v[98:101], v92 offset:10752
	ds_read_b128 v[106:109], v92 offset:11264
	ds_read2_b32 v[130:131], v136 offset0:128 offset1:144
	ds_write2st64_b32 v96, v46, v47 offset0:184 offset1:188
	s_waitcnt lgkmcnt(7)
	v_pk_mul_f32 v[36:37], v[90:91], v[114:115]
	v_pk_fma_f32 v[36:37], v[88:89], v[116:117], v[36:37]
	v_add_f32_e32 v38, v36, v37
	v_pk_mul_f32 v[40:41], v[122:123], v[132:133] op_sel:[0,1] op_sel_hi:[1,1]
	v_pk_mul_f32 v[42:43], v[124:125], v[132:133] op_sel:[0,1] op_sel_hi:[1,1]
	v_add_f32_dpp v38, v38, v38 quad_perm:[1,0,3,2] row_mask:0xf bank_mask:0xf bound_ctrl:1
	v_pk_fma_f32 v[40:41], v[90:91], v[110:111], v[40:41]
	v_pk_fma_f32 v[42:43], v[88:89], v[112:113], v[42:43]
	v_add_f32_dpp v38, v38, v38 quad_perm:[2,3,0,1] row_mask:0xf bank_mask:0xf bound_ctrl:1
	v_pk_mul_f32 v[44:45], v[90:91], v[50:51]
	v_pk_fma_f32 v[44:45], v[88:89], v[52:53], v[44:45]
	v_add_f32_dpp v38, v38, v38 row_half_mirror row_mask:0xf bank_mask:0xf bound_ctrl:1
	v_add_f32_e32 v48, v44, v45
	s_nop 0
	v_add_f32_dpp v38, v38, v38 row_mirror row_mask:0xf bank_mask:0xf bound_ctrl:1
	v_pk_fma_f32 v[90:91], v[118:119], v[38:39], v[40:41] op_sel_hi:[1,0,1]
	v_pk_fma_f32 v[88:89], v[120:121], v[38:39], v[42:43] op_sel_hi:[1,0,1]
	ds_read_b128 v[114:117], v92 offset:11776
	ds_read_b128 v[122:125], v92 offset:12288
	ds_read_b128 v[110:113], v92 offset:11520
	ds_read_b128 v[118:121], v92 offset:12032
	ds_read_b128 v[126:129], v92 offset:12544
	s_waitcnt lgkmcnt(5)
	v_pk_mul_f32 v[36:37], v[90:91], v[28:29]
	v_pk_fma_f32 v[36:37], v[88:89], v[30:31], v[36:37]
	v_add_f32_e32 v38, v36, v37
	v_pk_mul_f32 v[40:41], v[102:103], v[130:131] op_sel_hi:[1,0]
	v_pk_mul_f32 v[42:43], v[104:105], v[130:131] op_sel_hi:[1,0]
	v_add_f32_dpp v38, v38, v38 quad_perm:[1,0,3,2] row_mask:0xf bank_mask:0xf bound_ctrl:1
	v_pk_fma_f32 v[40:41], v[90:91], v[24:25], v[40:41]
	v_pk_fma_f32 v[42:43], v[88:89], v[26:27], v[42:43]
	v_add_f32_dpp v38, v38, v38 quad_perm:[2,3,0,1] row_mask:0xf bank_mask:0xf bound_ctrl:1
	v_pk_mul_f32 v[44:45], v[90:91], v[54:55]
	v_pk_fma_f32 v[44:45], v[88:89], v[56:57], v[44:45]
	v_add_f32_dpp v38, v38, v38 row_half_mirror row_mask:0xf bank_mask:0xf bound_ctrl:1
	v_add_f32_e32 v49, v44, v45
	s_nop 0
	v_add_f32_dpp v38, v38, v38 row_mirror row_mask:0xf bank_mask:0xf bound_ctrl:1
	v_pk_fma_f32 v[90:91], v[98:99], v[38:39], v[40:41] op_sel_hi:[1,0,1]
	v_pk_fma_f32 v[88:89], v[100:101], v[38:39], v[42:43] op_sel_hi:[1,0,1]
	ds_read_b128 v[28:31], v92 offset:13056
	ds_read_b128 v[102:105], v92 offset:13568
	ds_read_b128 v[24:27], v92 offset:12800
	ds_read_b128 v[98:101], v92 offset:13312
	ds_read_b128 v[50:53], v92 offset:13824
	ds_read2_b32 v[132:133], v136 offset0:160 offset1:176
	ds_write2st64_b32 v96, v48, v49 offset0:192 offset1:196
	s_waitcnt lgkmcnt(7)
	v_pk_mul_f32 v[36:37], v[90:91], v[114:115]
	v_pk_fma_f32 v[36:37], v[88:89], v[116:117], v[36:37]
	v_add_f32_e32 v38, v36, v37
	v_pk_mul_f32 v[40:41], v[122:123], v[130:131] op_sel:[0,1] op_sel_hi:[1,1]
	v_pk_mul_f32 v[42:43], v[124:125], v[130:131] op_sel:[0,1] op_sel_hi:[1,1]
	v_add_f32_dpp v38, v38, v38 quad_perm:[1,0,3,2] row_mask:0xf bank_mask:0xf bound_ctrl:1
	v_pk_fma_f32 v[40:41], v[90:91], v[110:111], v[40:41]
	v_pk_fma_f32 v[42:43], v[88:89], v[112:113], v[42:43]
	v_add_f32_dpp v38, v38, v38 quad_perm:[2,3,0,1] row_mask:0xf bank_mask:0xf bound_ctrl:1
	v_pk_mul_f32 v[44:45], v[90:91], v[106:107]
	v_pk_fma_f32 v[44:45], v[88:89], v[108:109], v[44:45]
	v_add_f32_dpp v38, v38, v38 row_half_mirror row_mask:0xf bank_mask:0xf bound_ctrl:1
	v_add_f32_e32 v46, v44, v45
	s_nop 0
	v_add_f32_dpp v38, v38, v38 row_mirror row_mask:0xf bank_mask:0xf bound_ctrl:1
	v_pk_fma_f32 v[90:91], v[118:119], v[38:39], v[40:41] op_sel_hi:[1,0,1]
	v_pk_fma_f32 v[88:89], v[120:121], v[38:39], v[42:43] op_sel_hi:[1,0,1]
	ds_read_b128 v[114:117], v92 offset:14336
	ds_read_b128 v[122:125], v92 offset:14848
	ds_read_b128 v[110:113], v92 offset:14080
	ds_read_b128 v[118:121], v92 offset:14592
	ds_read_b128 v[54:57], v92 offset:15104
	s_waitcnt lgkmcnt(5)
	v_pk_mul_f32 v[36:37], v[90:91], v[28:29]
	v_pk_fma_f32 v[36:37], v[88:89], v[30:31], v[36:37]
	v_add_f32_e32 v38, v36, v37
	v_pk_mul_f32 v[40:41], v[102:103], v[132:133] op_sel_hi:[1,0]
	v_pk_mul_f32 v[42:43], v[104:105], v[132:133] op_sel_hi:[1,0]
	v_add_f32_dpp v38, v38, v38 quad_perm:[1,0,3,2] row_mask:0xf bank_mask:0xf bound_ctrl:1
	v_pk_fma_f32 v[40:41], v[90:91], v[24:25], v[40:41]
	v_pk_fma_f32 v[42:43], v[88:89], v[26:27], v[42:43]
	v_add_f32_dpp v38, v38, v38 quad_perm:[2,3,0,1] row_mask:0xf bank_mask:0xf bound_ctrl:1
	v_pk_mul_f32 v[44:45], v[90:91], v[126:127]
	v_pk_fma_f32 v[44:45], v[88:89], v[128:129], v[44:45]
	v_add_f32_dpp v38, v38, v38 row_half_mirror row_mask:0xf bank_mask:0xf bound_ctrl:1
	v_add_f32_e32 v47, v44, v45
	s_nop 0
	v_add_f32_dpp v38, v38, v38 row_mirror row_mask:0xf bank_mask:0xf bound_ctrl:1
	v_pk_fma_f32 v[90:91], v[98:99], v[38:39], v[40:41] op_sel_hi:[1,0,1]
	v_pk_fma_f32 v[88:89], v[100:101], v[38:39], v[42:43] op_sel_hi:[1,0,1]
	ds_read_b128 v[28:31], v92 offset:15616
	ds_read_b128 v[102:105], v92 offset:16128
	ds_read_b128 v[24:27], v92 offset:15360
	ds_read_b128 v[98:101], v92 offset:15872
	ds_read_b128 v[106:109], v92 offset:16384
	ds_read2_b32 v[130:131], v136 offset0:192 offset1:208
	ds_write2st64_b32 v96, v46, v47 offset0:200 offset1:204
	s_waitcnt lgkmcnt(7)
	v_pk_mul_f32 v[36:37], v[90:91], v[114:115]
	v_pk_fma_f32 v[36:37], v[88:89], v[116:117], v[36:37]
	v_add_f32_e32 v38, v36, v37
	v_pk_mul_f32 v[40:41], v[122:123], v[132:133] op_sel:[0,1] op_sel_hi:[1,1]
	v_pk_mul_f32 v[42:43], v[124:125], v[132:133] op_sel:[0,1] op_sel_hi:[1,1]
	v_add_f32_dpp v38, v38, v38 quad_perm:[1,0,3,2] row_mask:0xf bank_mask:0xf bound_ctrl:1
	v_pk_fma_f32 v[40:41], v[90:91], v[110:111], v[40:41]
	v_pk_fma_f32 v[42:43], v[88:89], v[112:113], v[42:43]
	v_add_f32_dpp v38, v38, v38 quad_perm:[2,3,0,1] row_mask:0xf bank_mask:0xf bound_ctrl:1
	v_pk_mul_f32 v[44:45], v[90:91], v[50:51]
	v_pk_fma_f32 v[44:45], v[88:89], v[52:53], v[44:45]
	v_add_f32_dpp v38, v38, v38 row_half_mirror row_mask:0xf bank_mask:0xf bound_ctrl:1
	v_add_f32_e32 v48, v44, v45
	s_nop 0
	v_add_f32_dpp v38, v38, v38 row_mirror row_mask:0xf bank_mask:0xf bound_ctrl:1
	v_pk_fma_f32 v[90:91], v[118:119], v[38:39], v[40:41] op_sel_hi:[1,0,1]
	v_pk_fma_f32 v[88:89], v[120:121], v[38:39], v[42:43] op_sel_hi:[1,0,1]
	ds_read_b128 v[114:117], v92 offset:16896
	ds_read_b128 v[122:125], v92 offset:17408
	ds_read_b128 v[110:113], v92 offset:16640
	ds_read_b128 v[118:121], v92 offset:17152
	ds_read_b128 v[126:129], v92 offset:17664
	s_waitcnt lgkmcnt(5)
	v_pk_mul_f32 v[36:37], v[90:91], v[28:29]
	v_pk_fma_f32 v[36:37], v[88:89], v[30:31], v[36:37]
	v_add_f32_e32 v38, v36, v37
	v_pk_mul_f32 v[40:41], v[102:103], v[130:131] op_sel_hi:[1,0]
	v_pk_mul_f32 v[42:43], v[104:105], v[130:131] op_sel_hi:[1,0]
	v_add_f32_dpp v38, v38, v38 quad_perm:[1,0,3,2] row_mask:0xf bank_mask:0xf bound_ctrl:1
	v_pk_fma_f32 v[40:41], v[90:91], v[24:25], v[40:41]
	v_pk_fma_f32 v[42:43], v[88:89], v[26:27], v[42:43]
	v_add_f32_dpp v38, v38, v38 quad_perm:[2,3,0,1] row_mask:0xf bank_mask:0xf bound_ctrl:1
	v_pk_mul_f32 v[44:45], v[90:91], v[54:55]
	v_pk_fma_f32 v[44:45], v[88:89], v[56:57], v[44:45]
	v_add_f32_dpp v38, v38, v38 row_half_mirror row_mask:0xf bank_mask:0xf bound_ctrl:1
	v_add_f32_e32 v49, v44, v45
	s_nop 0
	v_add_f32_dpp v38, v38, v38 row_mirror row_mask:0xf bank_mask:0xf bound_ctrl:1
	v_pk_fma_f32 v[90:91], v[98:99], v[38:39], v[40:41] op_sel_hi:[1,0,1]
	v_pk_fma_f32 v[88:89], v[100:101], v[38:39], v[42:43] op_sel_hi:[1,0,1]
	ds_read_b128 v[28:31], v92 offset:18176
	ds_read_b128 v[102:105], v92 offset:18688
	ds_read_b128 v[24:27], v92 offset:17920
	ds_read_b128 v[98:101], v92 offset:18432
	ds_read_b128 v[50:53], v92 offset:18944
	ds_read2_b32 v[132:133], v136 offset0:224 offset1:240
	ds_write2st64_b32 v96, v48, v49 offset0:208 offset1:212
	s_waitcnt lgkmcnt(7)
	v_pk_mul_f32 v[36:37], v[90:91], v[114:115]
	v_pk_fma_f32 v[36:37], v[88:89], v[116:117], v[36:37]
	v_add_f32_e32 v38, v36, v37
	v_pk_mul_f32 v[40:41], v[122:123], v[130:131] op_sel:[0,1] op_sel_hi:[1,1]
	v_pk_mul_f32 v[42:43], v[124:125], v[130:131] op_sel:[0,1] op_sel_hi:[1,1]
	v_add_f32_dpp v38, v38, v38 quad_perm:[1,0,3,2] row_mask:0xf bank_mask:0xf bound_ctrl:1
	v_pk_fma_f32 v[40:41], v[90:91], v[110:111], v[40:41]
	v_pk_fma_f32 v[42:43], v[88:89], v[112:113], v[42:43]
	v_add_f32_dpp v38, v38, v38 quad_perm:[2,3,0,1] row_mask:0xf bank_mask:0xf bound_ctrl:1
	v_pk_mul_f32 v[44:45], v[90:91], v[106:107]
	v_pk_fma_f32 v[44:45], v[88:89], v[108:109], v[44:45]
	v_add_f32_dpp v38, v38, v38 row_half_mirror row_mask:0xf bank_mask:0xf bound_ctrl:1
	v_add_f32_e32 v46, v44, v45
	s_nop 0
	v_add_f32_dpp v38, v38, v38 row_mirror row_mask:0xf bank_mask:0xf bound_ctrl:1
	v_pk_fma_f32 v[90:91], v[118:119], v[38:39], v[40:41] op_sel_hi:[1,0,1]
	v_pk_fma_f32 v[88:89], v[120:121], v[38:39], v[42:43] op_sel_hi:[1,0,1]
	ds_read_b128 v[114:117], v92 offset:19456
	ds_read_b128 v[122:125], v92 offset:19968
	ds_read_b128 v[110:113], v92 offset:19200
	ds_read_b128 v[118:121], v92 offset:19712
	ds_read_b128 v[54:57], v92 offset:20224
	s_waitcnt lgkmcnt(5)
	v_pk_mul_f32 v[36:37], v[90:91], v[28:29]
	v_pk_fma_f32 v[36:37], v[88:89], v[30:31], v[36:37]
	v_add_f32_e32 v38, v36, v37
	v_pk_mul_f32 v[40:41], v[102:103], v[132:133] op_sel_hi:[1,0]
	v_pk_mul_f32 v[42:43], v[104:105], v[132:133] op_sel_hi:[1,0]
	v_add_f32_dpp v38, v38, v38 quad_perm:[1,0,3,2] row_mask:0xf bank_mask:0xf bound_ctrl:1
	v_pk_fma_f32 v[40:41], v[90:91], v[24:25], v[40:41]
	v_pk_fma_f32 v[42:43], v[88:89], v[26:27], v[42:43]
	v_add_f32_dpp v38, v38, v38 quad_perm:[2,3,0,1] row_mask:0xf bank_mask:0xf bound_ctrl:1
	v_pk_mul_f32 v[44:45], v[90:91], v[126:127]
	v_pk_fma_f32 v[44:45], v[88:89], v[128:129], v[44:45]
	v_add_f32_dpp v38, v38, v38 row_half_mirror row_mask:0xf bank_mask:0xf bound_ctrl:1
	v_add_f32_e32 v47, v44, v45
	s_nop 0
	v_add_f32_dpp v38, v38, v38 row_mirror row_mask:0xf bank_mask:0xf bound_ctrl:1
	v_pk_fma_f32 v[90:91], v[98:99], v[38:39], v[40:41] op_sel_hi:[1,0,1]
	v_pk_fma_f32 v[88:89], v[100:101], v[38:39], v[42:43] op_sel_hi:[1,0,1]
	ds_write2st64_b32 v96, v46, v47 offset0:216 offset1:220
	s_waitcnt lgkmcnt(1)
	v_pk_mul_f32 v[36:37], v[90:91], v[114:115]
	v_pk_fma_f32 v[36:37], v[88:89], v[116:117], v[36:37]
	v_add_f32_e32 v38, v36, v37
	v_pk_mul_f32 v[40:41], v[122:123], v[132:133] op_sel:[0,1] op_sel_hi:[1,1]
	v_pk_mul_f32 v[42:43], v[124:125], v[132:133] op_sel:[0,1] op_sel_hi:[1,1]
	v_add_f32_dpp v38, v38, v38 quad_perm:[1,0,3,2] row_mask:0xf bank_mask:0xf bound_ctrl:1
	v_pk_fma_f32 v[40:41], v[90:91], v[110:111], v[40:41]
	v_pk_fma_f32 v[42:43], v[88:89], v[112:113], v[42:43]
	v_add_f32_dpp v38, v38, v38 quad_perm:[2,3,0,1] row_mask:0xf bank_mask:0xf bound_ctrl:1
	v_pk_mul_f32 v[44:45], v[90:91], v[50:51]
	v_pk_fma_f32 v[44:45], v[88:89], v[52:53], v[44:45]
	v_add_f32_dpp v38, v38, v38 row_half_mirror row_mask:0xf bank_mask:0xf bound_ctrl:1
	v_add_f32_e32 v48, v44, v45
	s_nop 0
	v_add_f32_dpp v38, v38, v38 row_mirror row_mask:0xf bank_mask:0xf bound_ctrl:1
	v_pk_fma_f32 v[90:91], v[118:119], v[38:39], v[40:41] op_sel_hi:[1,0,1]
	v_pk_fma_f32 v[88:89], v[120:121], v[38:39], v[42:43] op_sel_hi:[1,0,1]
	v_pk_mul_f32 v[44:45], v[90:91], v[54:55]
	v_pk_fma_f32 v[44:45], v[88:89], v[56:57], v[44:45]
	v_add_f32_e32 v49, v44, v45
	ds_write2st64_b32 v96, v48, v49 offset0:224 offset1:228

.LBB0_660:
	s_andn2_saveexec_b64 s[46:47], s[46:47]
	s_cbranch_execz .LBB0_640
	v_add_u32_e32 v136, 0xa400, v95
	ds_read_b128 v[28:31], v92 offset:20736
	ds_read_b128 v[102:105], v92 offset:21248
	ds_read_b128 v[24:27], v92 offset:20480
	ds_read_b128 v[98:101], v92 offset:20992
	ds_read_b128 v[106:109], v92 offset:21504
	ds_read2_b32 v[130:131], v136 offset0:0 offset1:16
	ds_read_b128 v[114:117], v92 offset:22016
	ds_read_b128 v[122:125], v92 offset:22528
	ds_read_b128 v[110:113], v92 offset:21760
	ds_read_b128 v[118:121], v92 offset:22272
	ds_read_b128 v[126:129], v92 offset:22784
	s_waitcnt lgkmcnt(5)
	v_pk_mul_f32 v[36:37], v[90:91], v[28:29]
	v_pk_fma_f32 v[36:37], v[88:89], v[30:31], v[36:37]
	v_add_f32_e32 v38, v36, v37
	v_pk_mul_f32 v[40:41], v[102:103], v[130:131] op_sel_hi:[1,0]
	v_pk_mul_f32 v[42:43], v[104:105], v[130:131] op_sel_hi:[1,0]
	v_add_f32_dpp v38, v38, v38 quad_perm:[1,0,3,2] row_mask:0xf bank_mask:0xf bound_ctrl:1
	v_pk_fma_f32 v[40:41], v[90:91], v[24:25], v[40:41]
	v_pk_fma_f32 v[42:43], v[88:89], v[26:27], v[42:43]
	v_add_f32_dpp v38, v38, v38 quad_perm:[2,3,0,1] row_mask:0xf bank_mask:0xf bound_ctrl:1
	s_nop 1
	v_add_f32_dpp v38, v38, v38 row_half_mirror row_mask:0xf bank_mask:0xf bound_ctrl:1
	s_nop 1
	v_add_f32_dpp v38, v38, v38 row_mirror row_mask:0xf bank_mask:0xf bound_ctrl:1
	v_pk_fma_f32 v[90:91], v[98:99], v[38:39], v[40:41] op_sel_hi:[1,0,1]
	v_pk_fma_f32 v[88:89], v[100:101], v[38:39], v[42:43] op_sel_hi:[1,0,1]
	ds_read_b128 v[28:31], v92 offset:23296
	ds_read_b128 v[102:105], v92 offset:23808
	ds_read_b128 v[24:27], v92 offset:23040
	ds_read_b128 v[98:101], v92 offset:23552
	ds_read_b128 v[50:53], v92 offset:24064
	ds_read2_b32 v[132:133], v136 offset0:32 offset1:48
	s_waitcnt lgkmcnt(6)
	v_pk_mul_f32 v[36:37], v[90:91], v[114:115]
	v_pk_fma_f32 v[36:37], v[88:89], v[116:117], v[36:37]
	v_add_f32_e32 v38, v36, v37
	v_pk_mul_f32 v[40:41], v[122:123], v[130:131] op_sel:[0,1] op_sel_hi:[1,1]
	v_pk_mul_f32 v[42:43], v[124:125], v[130:131] op_sel:[0,1] op_sel_hi:[1,1]
	v_add_f32_dpp v38, v38, v38 quad_perm:[1,0,3,2] row_mask:0xf bank_mask:0xf bound_ctrl:1
	v_pk_fma_f32 v[40:41], v[90:91], v[110:111], v[40:41]
	v_pk_fma_f32 v[42:43], v[88:89], v[112:113], v[42:43]
	v_add_f32_dpp v38, v38, v38 quad_perm:[2,3,0,1] row_mask:0xf bank_mask:0xf bound_ctrl:1
	v_pk_mul_f32 v[44:45], v[90:91], v[106:107]
	v_pk_fma_f32 v[44:45], v[88:89], v[108:109], v[44:45]
	v_add_f32_dpp v38, v38, v38 row_half_mirror row_mask:0xf bank_mask:0xf bound_ctrl:1
	v_add_f32_e32 v46, v44, v45
	s_nop 0
	v_add_f32_dpp v38, v38, v38 row_mirror row_mask:0xf bank_mask:0xf bound_ctrl:1
	v_pk_fma_f32 v[90:91], v[118:119], v[38:39], v[40:41] op_sel_hi:[1,0,1]
	v_pk_fma_f32 v[88:89], v[120:121], v[38:39], v[42:43] op_sel_hi:[1,0,1]
	ds_read_b128 v[114:117], v92 offset:24576
	ds_read_b128 v[122:125], v92 offset:25088
	ds_read_b128 v[110:113], v92 offset:24320
	ds_read_b128 v[118:121], v92 offset:24832
	ds_read_b128 v[54:57], v92 offset:25344
	s_waitcnt lgkmcnt(5)
	v_pk_mul_f32 v[36:37], v[90:91], v[28:29]
	v_pk_fma_f32 v[36:37], v[88:89], v[30:31], v[36:37]
	v_add_f32_e32 v38, v36, v37
	v_pk_mul_f32 v[40:41], v[102:103], v[132:133] op_sel_hi:[1,0]
	v_pk_mul_f32 v[42:43], v[104:105], v[132:133] op_sel_hi:[1,0]
	v_add_f32_dpp v38, v38, v38 quad_perm:[1,0,3,2] row_mask:0xf bank_mask:0xf bound_ctrl:1
	v_pk_fma_f32 v[40:41], v[90:91], v[24:25], v[40:41]
	v_pk_fma_f32 v[42:43], v[88:89], v[26:27], v[42:43]
	v_add_f32_dpp v38, v38, v38 quad_perm:[2,3,0,1] row_mask:0xf bank_mask:0xf bound_ctrl:1
	v_pk_mul_f32 v[44:45], v[90:91], v[126:127]
	v_pk_fma_f32 v[44:45], v[88:89], v[128:129], v[44:45]
	v_add_f32_dpp v38, v38, v38 row_half_mirror row_mask:0xf bank_mask:0xf bound_ctrl:1
	v_add_f32_e32 v47, v44, v45
	s_nop 0
	v_add_f32_dpp v38, v38, v38 row_mirror row_mask:0xf bank_mask:0xf bound_ctrl:1
	v_pk_fma_f32 v[90:91], v[98:99], v[38:39], v[40:41] op_sel_hi:[1,0,1]
	v_pk_fma_f32 v[88:89], v[100:101], v[38:39], v[42:43] op_sel_hi:[1,0,1]
	ds_read_b128 v[28:31], v92 offset:25856
	ds_read_b128 v[102:105], v92 offset:26368
	ds_read_b128 v[24:27], v92 offset:25600
	ds_read_b128 v[98:101], v92 offset:26112
	ds_read_b128 v[106:109], v92 offset:26624
	ds_read2_b32 v[130:131], v136 offset0:64 offset1:80
	ds_write2st64_b32 v97, v46, v47 offset0:64 offset1:68
	s_waitcnt lgkmcnt(7)
	v_pk_mul_f32 v[36:37], v[90:91], v[114:115]
	v_pk_fma_f32 v[36:37], v[88:89], v[116:117], v[36:37]
	v_add_f32_e32 v38, v36, v37
	v_pk_mul_f32 v[40:41], v[122:123], v[132:133] op_sel:[0,1] op_sel_hi:[1,1]
	v_pk_mul_f32 v[42:43], v[124:125], v[132:133] op_sel:[0,1] op_sel_hi:[1,1]
	v_add_f32_dpp v38, v38, v38 quad_perm:[1,0,3,2] row_mask:0xf bank_mask:0xf bound_ctrl:1
	v_pk_fma_f32 v[40:41], v[90:91], v[110:111], v[40:41]
	v_pk_fma_f32 v[42:43], v[88:89], v[112:113], v[42:43]
	v_add_f32_dpp v38, v38, v38 quad_perm:[2,3,0,1] row_mask:0xf bank_mask:0xf bound_ctrl:1
	v_pk_mul_f32 v[44:45], v[90:91], v[50:51]
	v_pk_fma_f32 v[44:45], v[88:89], v[52:53], v[44:45]
	v_add_f32_dpp v38, v38, v38 row_half_mirror row_mask:0xf bank_mask:0xf bound_ctrl:1
	v_add_f32_e32 v48, v44, v45
	s_nop 0
	v_add_f32_dpp v38, v38, v38 row_mirror row_mask:0xf bank_mask:0xf bound_ctrl:1
	v_pk_fma_f32 v[90:91], v[118:119], v[38:39], v[40:41] op_sel_hi:[1,0,1]
	v_pk_fma_f32 v[88:89], v[120:121], v[38:39], v[42:43] op_sel_hi:[1,0,1]
	ds_read_b128 v[114:117], v92 offset:27136
	ds_read_b128 v[122:125], v92 offset:27648
	ds_read_b128 v[110:113], v92 offset:26880
	ds_read_b128 v[118:121], v92 offset:27392
	ds_read_b128 v[126:129], v92 offset:27904
	s_waitcnt lgkmcnt(5)
	v_pk_mul_f32 v[36:37], v[90:91], v[28:29]
	v_pk_fma_f32 v[36:37], v[88:89], v[30:31], v[36:37]
	v_add_f32_e32 v38, v36, v37
	v_pk_mul_f32 v[40:41], v[102:103], v[130:131] op_sel_hi:[1,0]
	v_pk_mul_f32 v[42:43], v[104:105], v[130:131] op_sel_hi:[1,0]
	v_add_f32_dpp v38, v38, v38 quad_perm:[1,0,3,2] row_mask:0xf bank_mask:0xf bound_ctrl:1
	v_pk_fma_f32 v[40:41], v[90:91], v[24:25], v[40:41]
	v_pk_fma_f32 v[42:43], v[88:89], v[26:27], v[42:43]
	v_add_f32_dpp v38, v38, v38 quad_perm:[2,3,0,1] row_mask:0xf bank_mask:0xf bound_ctrl:1
	v_pk_mul_f32 v[44:45], v[90:91], v[54:55]
	v_pk_fma_f32 v[44:45], v[88:89], v[56:57], v[44:45]
	v_add_f32_dpp v38, v38, v38 row_half_mirror row_mask:0xf bank_mask:0xf bound_ctrl:1
	v_add_f32_e32 v49, v44, v45
	s_nop 0
	v_add_f32_dpp v38, v38, v38 row_mirror row_mask:0xf bank_mask:0xf bound_ctrl:1
	v_pk_fma_f32 v[90:91], v[98:99], v[38:39], v[40:41] op_sel_hi:[1,0,1]
	v_pk_fma_f32 v[88:89], v[100:101], v[38:39], v[42:43] op_sel_hi:[1,0,1]
	ds_read_b128 v[28:31], v92 offset:28416
	ds_read_b128 v[102:105], v92 offset:28928
	ds_read_b128 v[24:27], v92 offset:28160
	ds_read_b128 v[98:101], v92 offset:28672
	ds_read_b128 v[50:53], v92 offset:29184
	ds_read2_b32 v[132:133], v136 offset0:96 offset1:112
	ds_write2st64_b32 v97, v48, v49 offset0:72 offset1:76
	s_waitcnt lgkmcnt(7)
	v_pk_mul_f32 v[36:37], v[90:91], v[114:115]
	v_pk_fma_f32 v[36:37], v[88:89], v[116:117], v[36:37]
	v_add_f32_e32 v38, v36, v37
	v_pk_mul_f32 v[40:41], v[122:123], v[130:131] op_sel:[0,1] op_sel_hi:[1,1]
	v_pk_mul_f32 v[42:43], v[124:125], v[130:131] op_sel:[0,1] op_sel_hi:[1,1]
	v_add_f32_dpp v38, v38, v38 quad_perm:[1,0,3,2] row_mask:0xf bank_mask:0xf bound_ctrl:1
	v_pk_fma_f32 v[40:41], v[90:91], v[110:111], v[40:41]
	v_pk_fma_f32 v[42:43], v[88:89], v[112:113], v[42:43]
	v_add_f32_dpp v38, v38, v38 quad_perm:[2,3,0,1] row_mask:0xf bank_mask:0xf bound_ctrl:1
	v_pk_mul_f32 v[44:45], v[90:91], v[106:107]
	v_pk_fma_f32 v[44:45], v[88:89], v[108:109], v[44:45]
	v_add_f32_dpp v38, v38, v38 row_half_mirror row_mask:0xf bank_mask:0xf bound_ctrl:1
	v_add_f32_e32 v46, v44, v45
	s_nop 0
	v_add_f32_dpp v38, v38, v38 row_mirror row_mask:0xf bank_mask:0xf bound_ctrl:1
	v_pk_fma_f32 v[90:91], v[118:119], v[38:39], v[40:41] op_sel_hi:[1,0,1]
	v_pk_fma_f32 v[88:89], v[120:121], v[38:39], v[42:43] op_sel_hi:[1,0,1]
	ds_read_b128 v[114:117], v92 offset:29696
	ds_read_b128 v[122:125], v92 offset:30208
	ds_read_b128 v[110:113], v92 offset:29440
	ds_read_b128 v[118:121], v92 offset:29952
	ds_read_b128 v[54:57], v92 offset:30464
	s_waitcnt lgkmcnt(5)
	v_pk_mul_f32 v[36:37], v[90:91], v[28:29]
	v_pk_fma_f32 v[36:37], v[88:89], v[30:31], v[36:37]
	v_add_f32_e32 v38, v36, v37
	v_pk_mul_f32 v[40:41], v[102:103], v[132:133] op_sel_hi:[1,0]
	v_pk_mul_f32 v[42:43], v[104:105], v[132:133] op_sel_hi:[1,0]
	v_add_f32_dpp v38, v38, v38 quad_perm:[1,0,3,2] row_mask:0xf bank_mask:0xf bound_ctrl:1
	v_pk_fma_f32 v[40:41], v[90:91], v[24:25], v[40:41]
	v_pk_fma_f32 v[42:43], v[88:89], v[26:27], v[42:43]
	v_add_f32_dpp v38, v38, v38 quad_perm:[2,3,0,1] row_mask:0xf bank_mask:0xf bound_ctrl:1
	v_pk_mul_f32 v[44:45], v[90:91], v[126:127]
	v_pk_fma_f32 v[44:45], v[88:89], v[128:129], v[44:45]
	v_add_f32_dpp v38, v38, v38 row_half_mirror row_mask:0xf bank_mask:0xf bound_ctrl:1
	v_add_f32_e32 v47, v44, v45
	s_nop 0
	v_add_f32_dpp v38, v38, v38 row_mirror row_mask:0xf bank_mask:0xf bound_ctrl:1
	v_pk_fma_f32 v[90:91], v[98:99], v[38:39], v[40:41] op_sel_hi:[1,0,1]
	v_pk_fma_f32 v[88:89], v[100:101], v[38:39], v[42:43] op_sel_hi:[1,0,1]
	ds_read_b128 v[28:31], v92 offset:30976
	ds_read_b128 v[102:105], v92 offset:31488
	ds_read_b128 v[24:27], v92 offset:30720
	ds_read_b128 v[98:101], v92 offset:31232
	ds_read_b128 v[106:109], v92 offset:31744
	ds_read2_b32 v[130:131], v136 offset0:128 offset1:144
	ds_write2st64_b32 v97, v46, v47 offset0:80 offset1:84
	s_waitcnt lgkmcnt(7)
	v_pk_mul_f32 v[36:37], v[90:91], v[114:115]
	v_pk_fma_f32 v[36:37], v[88:89], v[116:117], v[36:37]
	v_add_f32_e32 v38, v36, v37
	v_pk_mul_f32 v[40:41], v[122:123], v[132:133] op_sel:[0,1] op_sel_hi:[1,1]
	v_pk_mul_f32 v[42:43], v[124:125], v[132:133] op_sel:[0,1] op_sel_hi:[1,1]
	v_add_f32_dpp v38, v38, v38 quad_perm:[1,0,3,2] row_mask:0xf bank_mask:0xf bound_ctrl:1
	v_pk_fma_f32 v[40:41], v[90:91], v[110:111], v[40:41]
	v_pk_fma_f32 v[42:43], v[88:89], v[112:113], v[42:43]
	v_add_f32_dpp v38, v38, v38 quad_perm:[2,3,0,1] row_mask:0xf bank_mask:0xf bound_ctrl:1
	v_pk_mul_f32 v[44:45], v[90:91], v[50:51]
	v_pk_fma_f32 v[44:45], v[88:89], v[52:53], v[44:45]
	v_add_f32_dpp v38, v38, v38 row_half_mirror row_mask:0xf bank_mask:0xf bound_ctrl:1
	v_add_f32_e32 v48, v44, v45
	s_nop 0
	v_add_f32_dpp v38, v38, v38 row_mirror row_mask:0xf bank_mask:0xf bound_ctrl:1
	v_pk_fma_f32 v[90:91], v[118:119], v[38:39], v[40:41] op_sel_hi:[1,0,1]
	v_pk_fma_f32 v[88:89], v[120:121], v[38:39], v[42:43] op_sel_hi:[1,0,1]
	ds_read_b128 v[114:117], v92 offset:32256
	ds_read_b128 v[122:125], v92 offset:32768
	ds_read_b128 v[110:113], v92 offset:32000
	ds_read_b128 v[118:121], v92 offset:32512
	ds_read_b128 v[126:129], v92 offset:33024
	s_waitcnt lgkmcnt(5)
	v_pk_mul_f32 v[36:37], v[90:91], v[28:29]
	v_pk_fma_f32 v[36:37], v[88:89], v[30:31], v[36:37]
	v_add_f32_e32 v38, v36, v37
	v_pk_mul_f32 v[40:41], v[102:103], v[130:131] op_sel_hi:[1,0]
	v_pk_mul_f32 v[42:43], v[104:105], v[130:131] op_sel_hi:[1,0]
	v_add_f32_dpp v38, v38, v38 quad_perm:[1,0,3,2] row_mask:0xf bank_mask:0xf bound_ctrl:1
	v_pk_fma_f32 v[40:41], v[90:91], v[24:25], v[40:41]
	v_pk_fma_f32 v[42:43], v[88:89], v[26:27], v[42:43]
	v_add_f32_dpp v38, v38, v38 quad_perm:[2,3,0,1] row_mask:0xf bank_mask:0xf bound_ctrl:1
	v_pk_mul_f32 v[44:45], v[90:91], v[54:55]
	v_pk_fma_f32 v[44:45], v[88:89], v[56:57], v[44:45]
	v_add_f32_dpp v38, v38, v38 row_half_mirror row_mask:0xf bank_mask:0xf bound_ctrl:1
	v_add_f32_e32 v49, v44, v45
	s_nop 0
	v_add_f32_dpp v38, v38, v38 row_mirror row_mask:0xf bank_mask:0xf bound_ctrl:1
	v_pk_fma_f32 v[90:91], v[98:99], v[38:39], v[40:41] op_sel_hi:[1,0,1]
	v_pk_fma_f32 v[88:89], v[100:101], v[38:39], v[42:43] op_sel_hi:[1,0,1]
	ds_read_b128 v[28:31], v92 offset:33536
	ds_read_b128 v[102:105], v92 offset:34048
	ds_read_b128 v[24:27], v92 offset:33280
	ds_read_b128 v[98:101], v92 offset:33792
	ds_read_b128 v[50:53], v92 offset:34304
	ds_read2_b32 v[132:133], v136 offset0:160 offset1:176
	ds_write2st64_b32 v97, v48, v49 offset0:88 offset1:92
	s_waitcnt lgkmcnt(7)
	v_pk_mul_f32 v[36:37], v[90:91], v[114:115]
	v_pk_fma_f32 v[36:37], v[88:89], v[116:117], v[36:37]
	v_add_f32_e32 v38, v36, v37
	v_pk_mul_f32 v[40:41], v[122:123], v[130:131] op_sel:[0,1] op_sel_hi:[1,1]
	v_pk_mul_f32 v[42:43], v[124:125], v[130:131] op_sel:[0,1] op_sel_hi:[1,1]
	v_add_f32_dpp v38, v38, v38 quad_perm:[1,0,3,2] row_mask:0xf bank_mask:0xf bound_ctrl:1
	v_pk_fma_f32 v[40:41], v[90:91], v[110:111], v[40:41]
	v_pk_fma_f32 v[42:43], v[88:89], v[112:113], v[42:43]
	v_add_f32_dpp v38, v38, v38 quad_perm:[2,3,0,1] row_mask:0xf bank_mask:0xf bound_ctrl:1
	v_pk_mul_f32 v[44:45], v[90:91], v[106:107]
	v_pk_fma_f32 v[44:45], v[88:89], v[108:109], v[44:45]
	v_add_f32_dpp v38, v38, v38 row_half_mirror row_mask:0xf bank_mask:0xf bound_ctrl:1
	v_add_f32_e32 v46, v44, v45
	s_nop 0
	v_add_f32_dpp v38, v38, v38 row_mirror row_mask:0xf bank_mask:0xf bound_ctrl:1
	v_pk_fma_f32 v[90:91], v[118:119], v[38:39], v[40:41] op_sel_hi:[1,0,1]
	v_pk_fma_f32 v[88:89], v[120:121], v[38:39], v[42:43] op_sel_hi:[1,0,1]
	ds_read_b128 v[114:117], v92 offset:34816
	ds_read_b128 v[122:125], v92 offset:35328
	ds_read_b128 v[110:113], v92 offset:34560
	ds_read_b128 v[118:121], v92 offset:35072
	ds_read_b128 v[54:57], v92 offset:35584
	s_waitcnt lgkmcnt(5)
	v_pk_mul_f32 v[36:37], v[90:91], v[28:29]
	v_pk_fma_f32 v[36:37], v[88:89], v[30:31], v[36:37]
	v_add_f32_e32 v38, v36, v37
	v_pk_mul_f32 v[40:41], v[102:103], v[132:133] op_sel_hi:[1,0]
	v_pk_mul_f32 v[42:43], v[104:105], v[132:133] op_sel_hi:[1,0]
	v_add_f32_dpp v38, v38, v38 quad_perm:[1,0,3,2] row_mask:0xf bank_mask:0xf bound_ctrl:1
	v_pk_fma_f32 v[40:41], v[90:91], v[24:25], v[40:41]
	v_pk_fma_f32 v[42:43], v[88:89], v[26:27], v[42:43]
	v_add_f32_dpp v38, v38, v38 quad_perm:[2,3,0,1] row_mask:0xf bank_mask:0xf bound_ctrl:1
	v_pk_mul_f32 v[44:45], v[90:91], v[126:127]
	v_pk_fma_f32 v[44:45], v[88:89], v[128:129], v[44:45]
	v_add_f32_dpp v38, v38, v38 row_half_mirror row_mask:0xf bank_mask:0xf bound_ctrl:1
	v_add_f32_e32 v47, v44, v45
	s_nop 0
	v_add_f32_dpp v38, v38, v38 row_mirror row_mask:0xf bank_mask:0xf bound_ctrl:1
	v_pk_fma_f32 v[90:91], v[98:99], v[38:39], v[40:41] op_sel_hi:[1,0,1]
	v_pk_fma_f32 v[88:89], v[100:101], v[38:39], v[42:43] op_sel_hi:[1,0,1]
	ds_read_b128 v[28:31], v92 offset:36096
	ds_read_b128 v[102:105], v92 offset:36608
	ds_read_b128 v[24:27], v92 offset:35840
	ds_read_b128 v[98:101], v92 offset:36352
	ds_read_b128 v[106:109], v92 offset:36864
	ds_read2_b32 v[130:131], v136 offset0:192 offset1:208
	ds_write2st64_b32 v97, v46, v47 offset0:96 offset1:100
	s_waitcnt lgkmcnt(7)
	v_pk_mul_f32 v[36:37], v[90:91], v[114:115]
	v_pk_fma_f32 v[36:37], v[88:89], v[116:117], v[36:37]
	v_add_f32_e32 v38, v36, v37
	v_pk_mul_f32 v[40:41], v[122:123], v[132:133] op_sel:[0,1] op_sel_hi:[1,1]
	v_pk_mul_f32 v[42:43], v[124:125], v[132:133] op_sel:[0,1] op_sel_hi:[1,1]
	v_add_f32_dpp v38, v38, v38 quad_perm:[1,0,3,2] row_mask:0xf bank_mask:0xf bound_ctrl:1
	v_pk_fma_f32 v[40:41], v[90:91], v[110:111], v[40:41]
	v_pk_fma_f32 v[42:43], v[88:89], v[112:113], v[42:43]
	v_add_f32_dpp v38, v38, v38 quad_perm:[2,3,0,1] row_mask:0xf bank_mask:0xf bound_ctrl:1
	v_pk_mul_f32 v[44:45], v[90:91], v[50:51]
	v_pk_fma_f32 v[44:45], v[88:89], v[52:53], v[44:45]
	v_add_f32_dpp v38, v38, v38 row_half_mirror row_mask:0xf bank_mask:0xf bound_ctrl:1
	v_add_f32_e32 v48, v44, v45
	s_nop 0
	v_add_f32_dpp v38, v38, v38 row_mirror row_mask:0xf bank_mask:0xf bound_ctrl:1
	v_pk_fma_f32 v[90:91], v[118:119], v[38:39], v[40:41] op_sel_hi:[1,0,1]
	v_pk_fma_f32 v[88:89], v[120:121], v[38:39], v[42:43] op_sel_hi:[1,0,1]
	ds_read_b128 v[114:117], v92 offset:37376
	ds_read_b128 v[122:125], v92 offset:37888
	ds_read_b128 v[110:113], v92 offset:37120
	ds_read_b128 v[118:121], v92 offset:37632
	ds_read_b128 v[126:129], v92 offset:38144
	s_waitcnt lgkmcnt(5)
	v_pk_mul_f32 v[36:37], v[90:91], v[28:29]
	v_pk_fma_f32 v[36:37], v[88:89], v[30:31], v[36:37]
	v_add_f32_e32 v38, v36, v37
	v_pk_mul_f32 v[40:41], v[102:103], v[130:131] op_sel_hi:[1,0]
	v_pk_mul_f32 v[42:43], v[104:105], v[130:131] op_sel_hi:[1,0]
	v_add_f32_dpp v38, v38, v38 quad_perm:[1,0,3,2] row_mask:0xf bank_mask:0xf bound_ctrl:1
	v_pk_fma_f32 v[40:41], v[90:91], v[24:25], v[40:41]
	v_pk_fma_f32 v[42:43], v[88:89], v[26:27], v[42:43]
	v_add_f32_dpp v38, v38, v38 quad_perm:[2,3,0,1] row_mask:0xf bank_mask:0xf bound_ctrl:1
	v_pk_mul_f32 v[44:45], v[90:91], v[54:55]
	v_pk_fma_f32 v[44:45], v[88:89], v[56:57], v[44:45]
	v_add_f32_dpp v38, v38, v38 row_half_mirror row_mask:0xf bank_mask:0xf bound_ctrl:1
	v_add_f32_e32 v49, v44, v45
	s_nop 0
	v_add_f32_dpp v38, v38, v38 row_mirror row_mask:0xf bank_mask:0xf bound_ctrl:1
	v_pk_fma_f32 v[90:91], v[98:99], v[38:39], v[40:41] op_sel_hi:[1,0,1]
	v_pk_fma_f32 v[88:89], v[100:101], v[38:39], v[42:43] op_sel_hi:[1,0,1]
	ds_read_b128 v[28:31], v92 offset:38656
	ds_read_b128 v[102:105], v92 offset:39168
	ds_read_b128 v[24:27], v92 offset:38400
	ds_read_b128 v[98:101], v92 offset:38912
	ds_read_b128 v[50:53], v92 offset:39424
	ds_read2_b32 v[132:133], v136 offset0:224 offset1:240
	ds_write2st64_b32 v97, v48, v49 offset0:104 offset1:108
	s_waitcnt lgkmcnt(7)
	v_pk_mul_f32 v[36:37], v[90:91], v[114:115]
	v_pk_fma_f32 v[36:37], v[88:89], v[116:117], v[36:37]
	v_add_f32_e32 v38, v36, v37
	v_pk_mul_f32 v[40:41], v[122:123], v[130:131] op_sel:[0,1] op_sel_hi:[1,1]
	v_pk_mul_f32 v[42:43], v[124:125], v[130:131] op_sel:[0,1] op_sel_hi:[1,1]
	v_add_f32_dpp v38, v38, v38 quad_perm:[1,0,3,2] row_mask:0xf bank_mask:0xf bound_ctrl:1
	v_pk_fma_f32 v[40:41], v[90:91], v[110:111], v[40:41]
	v_pk_fma_f32 v[42:43], v[88:89], v[112:113], v[42:43]
	v_add_f32_dpp v38, v38, v38 quad_perm:[2,3,0,1] row_mask:0xf bank_mask:0xf bound_ctrl:1
	v_pk_mul_f32 v[44:45], v[90:91], v[106:107]
	v_pk_fma_f32 v[44:45], v[88:89], v[108:109], v[44:45]
	v_add_f32_dpp v38, v38, v38 row_half_mirror row_mask:0xf bank_mask:0xf bound_ctrl:1
	v_add_f32_e32 v46, v44, v45
	s_nop 0
	v_add_f32_dpp v38, v38, v38 row_mirror row_mask:0xf bank_mask:0xf bound_ctrl:1
	v_pk_fma_f32 v[90:91], v[118:119], v[38:39], v[40:41] op_sel_hi:[1,0,1]
	v_pk_fma_f32 v[88:89], v[120:121], v[38:39], v[42:43] op_sel_hi:[1,0,1]
	ds_read_b128 v[114:117], v92 offset:39936
	ds_read_b128 v[122:125], v92 offset:40448
	ds_read_b128 v[110:113], v92 offset:39680
	ds_read_b128 v[118:121], v92 offset:40192
	ds_read_b128 v[54:57], v92 offset:40704
	s_waitcnt lgkmcnt(5)
	v_pk_mul_f32 v[36:37], v[90:91], v[28:29]
	v_pk_fma_f32 v[36:37], v[88:89], v[30:31], v[36:37]
	v_add_f32_e32 v38, v36, v37
	v_pk_mul_f32 v[40:41], v[102:103], v[132:133] op_sel_hi:[1,0]
	v_pk_mul_f32 v[42:43], v[104:105], v[132:133] op_sel_hi:[1,0]
	v_add_f32_dpp v38, v38, v38 quad_perm:[1,0,3,2] row_mask:0xf bank_mask:0xf bound_ctrl:1
	v_pk_fma_f32 v[40:41], v[90:91], v[24:25], v[40:41]
	v_pk_fma_f32 v[42:43], v[88:89], v[26:27], v[42:43]
	v_add_f32_dpp v38, v38, v38 quad_perm:[2,3,0,1] row_mask:0xf bank_mask:0xf bound_ctrl:1
	v_pk_mul_f32 v[44:45], v[90:91], v[126:127]
	v_pk_fma_f32 v[44:45], v[88:89], v[128:129], v[44:45]
	v_add_f32_dpp v38, v38, v38 row_half_mirror row_mask:0xf bank_mask:0xf bound_ctrl:1
	v_add_f32_e32 v47, v44, v45
	s_nop 0
	v_add_f32_dpp v38, v38, v38 row_mirror row_mask:0xf bank_mask:0xf bound_ctrl:1
	v_pk_fma_f32 v[90:91], v[98:99], v[38:39], v[40:41] op_sel_hi:[1,0,1]
	v_pk_fma_f32 v[88:89], v[100:101], v[38:39], v[42:43] op_sel_hi:[1,0,1]
	ds_write2st64_b32 v97, v46, v47 offset0:112 offset1:116
	s_waitcnt lgkmcnt(1)
	v_pk_mul_f32 v[36:37], v[90:91], v[114:115]
	v_pk_fma_f32 v[36:37], v[88:89], v[116:117], v[36:37]
	v_add_f32_e32 v38, v36, v37
	v_pk_mul_f32 v[40:41], v[122:123], v[132:133] op_sel:[0,1] op_sel_hi:[1,1]
	v_pk_mul_f32 v[42:43], v[124:125], v[132:133] op_sel:[0,1] op_sel_hi:[1,1]
	v_add_f32_dpp v38, v38, v38 quad_perm:[1,0,3,2] row_mask:0xf bank_mask:0xf bound_ctrl:1
	v_pk_fma_f32 v[40:41], v[90:91], v[110:111], v[40:41]
	v_pk_fma_f32 v[42:43], v[88:89], v[112:113], v[42:43]
	v_add_f32_dpp v38, v38, v38 quad_perm:[2,3,0,1] row_mask:0xf bank_mask:0xf bound_ctrl:1
	v_pk_mul_f32 v[44:45], v[90:91], v[50:51]
	v_pk_fma_f32 v[44:45], v[88:89], v[52:53], v[44:45]
	v_add_f32_dpp v38, v38, v38 row_half_mirror row_mask:0xf bank_mask:0xf bound_ctrl:1
	v_add_f32_e32 v48, v44, v45
	s_nop 0
	v_add_f32_dpp v38, v38, v38 row_mirror row_mask:0xf bank_mask:0xf bound_ctrl:1
	v_pk_fma_f32 v[90:91], v[118:119], v[38:39], v[40:41] op_sel_hi:[1,0,1]
	v_pk_fma_f32 v[88:89], v[120:121], v[38:39], v[42:43] op_sel_hi:[1,0,1]
	v_pk_mul_f32 v[44:45], v[90:91], v[54:55]
	v_pk_fma_f32 v[44:45], v[88:89], v[56:57], v[44:45]
	v_add_f32_e32 v49, v44, v45
	ds_write2st64_b32 v97, v48, v49 offset0:120 offset1:124
	s_branch .LBB0_640
